# rmsnorm wave reduction: xor-8/4/2/1 butterfly steps via DPP row ops instead of ds_bpermute round trips (same pairing order, bit-identical sums), on top of the four-tail GEMM version
# speedup vs baseline: 1.0034x; 1.0034x over previous
; DI float wave_sum(float v) {
; #pragma unroll
;   for (int o = 32; o >= 1; o >>= 1) v += __shfl_xor(v, o);
;   return v;
; DI void phase_rmsnorm(const float* x, const float* g, bf16* hn) {
;     ...
;   for (int t = blockIdx.x * 4 + w; t < T_; t += gridDim.x * 4) {
;     const float4* xr = (const float4*)(x + (size_t)t * DM);
;     float4 v[4];
;     float ss = 0.f;
; #pragma unroll
;     for (int i = 0; i < 4; ++i) {
;       v[i] = xr[lane + 64 * i];
;       ss += v[i].x * v[i].x + v[i].y * v[i].y + v[i].z * v[i].z + v[i].w * v[i].w;
;     }
;     ss = wave_sum(ss);
;     const float r = rsqrtf(ss * (1.f / DM) + EPS);
.LBB0_35:
	v_ashrrev_i32_e32 v1, 31, v0
	v_lshlrev_b64 v[18:19], 12, v[0:1]
	v_lshl_add_u64 v[30:31], v[4:5], 0, v[18:19]
	global_load_dwordx4 v[18:21], v[30:31], off
	global_load_dwordx4 v[22:25], v[30:31], off offset:1024
	global_load_dwordx4 v[26:29], v[30:31], off offset:2048
	s_nop 0
	global_load_dwordx4 v[30:33], v[30:31], off offset:3072
	s_nop 0
	global_load_dwordx4 v[34:37], v[2:3], off
	v_mov_b32_e32 v11, v137
	s_waitcnt vmcnt(0)
	v_mov_b32_e32 v44, v19
	v_mov_b32_e32 v45, v23
	v_mov_b32_e32 v42, v18
	v_mov_b32_e32 v43, v22
	v_mov_b32_e32 v52, v27
	v_mov_b32_e32 v53, v31
	v_pk_mul_f32 v[44:45], v[44:45], v[44:45]
	v_mov_b32_e32 v38, v20
	v_mov_b32_e32 v39, v24
	v_mov_b32_e32 v50, v26
	v_mov_b32_e32 v51, v30
	v_pk_mul_f32 v[52:53], v[52:53], v[52:53]
	v_pk_fma_f32 v[42:43], v[42:43], v[42:43], v[44:45]
	v_mov_b32_e32 v40, v21
	v_mov_b32_e32 v41, v25
	v_mov_b32_e32 v46, v28
	v_mov_b32_e32 v47, v32
	v_pk_fma_f32 v[44:45], v[50:51], v[50:51], v[52:53]
	v_pk_fma_f32 v[38:39], v[38:39], v[38:39], v[42:43]
	v_mov_b32_e32 v48, v29
	v_mov_b32_e32 v49, v33
	v_pk_fma_f32 v[42:43], v[46:47], v[46:47], v[44:45]
	v_pk_fma_f32 v[38:39], v[40:41], v[40:41], v[38:39]
	v_pk_fma_f32 v[40:41], v[48:49], v[48:49], v[42:43]
	v_add_f32_e32 v7, v38, v39
	v_add_f32_e32 v7, v7, v40
	v_add_f32_e32 v7, v7, v41
	ds_bpermute_b32 v9, v12, v7
	v_lshlrev_b64 v[38:39], 11, v[0:1]
	v_lshl_add_u64 v[38:39], s[84:85], 0, v[38:39]
	v_lshl_add_u64 v[40:41], v[38:39], 0, v[136:137]
	v_add_u32_e32 v0, s26, v0
	s_waitcnt lgkmcnt(0)
	v_add_f32_e32 v7, v7, v9
	ds_bpermute_b32 v9, v13, v7
	s_waitcnt lgkmcnt(0)
	v_add_f32_e32 v7, v7, v9
	s_nop 1
	v_add_f32_dpp v7, v7, v7 row_ror:8 row_mask:0xf bank_mask:0xf
	s_nop 1
	v_add_f32_dpp v7, v7, v7 row_ror:4 row_mask:0xf bank_mask:0xf
	s_nop 1
	v_add_f32_dpp v7, v7, v7 quad_perm:[2,3,0,1] row_mask:0xf bank_mask:0xf
	s_nop 1
	v_add_f32_dpp v7, v7, v7 quad_perm:[1,0,3,2] row_mask:0xf bank_mask:0xf
	v_fmamk_f32 v7, v7, 0x3a800000, v165
	v_mul_f32_e32 v9, 0x4b800000, v7
	v_cmp_gt_f32_e32 vcc, s2, v7
	s_nop 1
	v_cndmask_b32_e32 v7, v7, v9, vcc
	v_rsq_f32_e32 v7, v7
	v_mov_b32_e32 v9, v137
	v_mul_f32_e32 v1, 0x45800000, v7
	v_cndmask_b32_e32 v42, v7, v1, vcc
	v_pk_mul_f32 v[18:19], v[18:19], v[42:43] op_sel_hi:[1,0]
	v_pk_mul_f32 v[20:21], v[20:21], v[42:43] op_sel_hi:[1,0]
	v_pk_mul_f32 v[18:19], v[34:35], v[18:19]
	v_pk_mul_f32 v[20:21], v[36:37], v[20:21]
	v_cvt_pk_bf16_f32 v18, v18, v19
	v_cvt_pk_bf16_f32 v19, v20, v21
	global_store_dwordx2 v[40:41], v[18:19], off
	global_load_dwordx4 v[18:21], v[2:3], off offset:1024
	v_pk_mul_f32 v[22:23], v[22:23], v[42:43] op_sel_hi:[1,0]
	v_pk_mul_f32 v[24:25], v[24:25], v[42:43] op_sel_hi:[1,0]
	v_mov_b32_e32 v7, v137
	v_lshl_add_u64 v[34:35], v[38:39], 0, v[6:7]
	v_cmp_lt_i32_e32 vcc, s3, v0
	s_or_b64 s[10:11], vcc, s[10:11]
	s_waitcnt vmcnt(0)
	v_pk_mul_f32 v[18:19], v[18:19], v[22:23]
	v_pk_mul_f32 v[20:21], v[20:21], v[24:25]
	v_cvt_pk_bf16_f32 v18, v18, v19
	v_cvt_pk_bf16_f32 v19, v20, v21
	global_store_dwordx2 v[34:35], v[18:19], off
	global_load_dwordx4 v[18:21], v[2:3], off offset:2048
	v_pk_mul_f32 v[24:25], v[26:27], v[42:43] op_sel_hi:[1,0]
	v_pk_mul_f32 v[26:27], v[28:29], v[42:43] op_sel_hi:[1,0]
	v_lshl_add_u64 v[22:23], v[38:39], 0, v[8:9]
	s_waitcnt vmcnt(0)
	v_pk_mul_f32 v[18:19], v[18:19], v[24:25]
	v_pk_mul_f32 v[20:21], v[26:27], v[20:21]
	v_cvt_pk_bf16_f32 v18, v18, v19
	v_cvt_pk_bf16_f32 v19, v20, v21
	global_store_dwordx2 v[22:23], v[18:19], off
	global_load_dwordx4 v[18:21], v[2:3], off offset:3072
	v_pk_mul_f32 v[24:25], v[30:31], v[42:43] op_sel_hi:[1,0]
	v_pk_mul_f32 v[26:27], v[32:33], v[42:43] op_sel_hi:[1,0]
	v_lshl_add_u64 v[22:23], v[38:39], 0, v[10:11]
	s_waitcnt vmcnt(0)
	v_pk_mul_f32 v[18:19], v[24:25], v[18:19]
	v_pk_mul_f32 v[20:21], v[26:27], v[20:21]
	v_cvt_pk_bf16_f32 v18, v18, v19
	v_cvt_pk_bf16_f32 v19, v20, v21
	global_store_dwordx2 v[22:23], v[18:19], off
	s_andn2_b64 exec, exec, s[10:11]
	s_cbranch_execnz .LBB0_35

; DI unsigned pk2(float a, float b) { f32x2 v = {a, b}; return __builtin_bit_cast(unsigned, __builtin_convertvector(v, bf16x2)); }
; DI float wave_sum(float v) {
; #pragma unroll
;   for (int o = 32; o >= 1; o >>= 1) v += __shfl_xor(v, o);
;   return v;
; DI void phase_rmsnorm(const float* x, const float* g, bf16* hn) {
;     ...
;   for (int t = blockIdx.x * 4 + w; t < T_; t += gridDim.x * 4) {
;     const float4* xr = (const float4*)(x + (size_t)t * DM);
;     float4 v[4];
;     float ss = 0.f;
; #pragma unroll
;     for (int i = 0; i < 4; ++i) {
;       v[i] = xr[lane + 64 * i];
;       ss += v[i].x * v[i].x + v[i].y * v[i].y + v[i].z * v[i].z + v[i].w * v[i].w;
;     }
;     ss = wave_sum(ss);
;     const float r = rsqrtf(ss * (1.f / DM) + EPS);
; #pragma unroll
;     for (int i = 0; i < 4; ++i) {
;       const float4 gg = ((const float4*)g)[lane + 64 * i];
;       u32x2 o;
;       o.x = pk2(v[i].x * r * gg.x, v[i].y * r * gg.y);
;       o.y = pk2(v[i].z * r * gg.z, v[i].w * r * gg.w);
;       *(u32x2*)(hn + (size_t)t * DM + (lane + 64 * i) * 4) = o;
;     }
.LBB0_180:
	v_ashrrev_i32_e32 v1, 31, v0
	v_lshlrev_b64 v[18:19], 12, v[0:1]
	v_lshl_add_u64 v[30:31], v[4:5], 0, v[18:19]
	global_load_dwordx4 v[18:21], v[30:31], off
	global_load_dwordx4 v[22:25], v[30:31], off offset:1024
	global_load_dwordx4 v[26:29], v[30:31], off offset:2048
	s_nop 0
	global_load_dwordx4 v[30:33], v[30:31], off offset:3072
	s_nop 0
	global_load_dwordx4 v[34:37], v[2:3], off
	v_mov_b32_e32 v11, v137
	s_waitcnt vmcnt(4)
	v_mov_b32_e32 v44, v19
	s_waitcnt vmcnt(3)
	v_mov_b32_e32 v45, v23
	v_mov_b32_e32 v42, v18
	v_mov_b32_e32 v43, v22
	s_waitcnt vmcnt(2)
	v_mov_b32_e32 v52, v27
	s_waitcnt vmcnt(1)
	v_mov_b32_e32 v53, v31
	v_pk_mul_f32 v[44:45], v[44:45], v[44:45]
	v_mov_b32_e32 v38, v20
	v_mov_b32_e32 v39, v24
	v_mov_b32_e32 v50, v26
	v_mov_b32_e32 v51, v30
	v_pk_mul_f32 v[52:53], v[52:53], v[52:53]
	v_pk_fma_f32 v[42:43], v[42:43], v[42:43], v[44:45]
	v_mov_b32_e32 v40, v21
	v_mov_b32_e32 v41, v25
	v_mov_b32_e32 v46, v28
	v_mov_b32_e32 v47, v32
	v_pk_fma_f32 v[44:45], v[50:51], v[50:51], v[52:53]
	v_pk_fma_f32 v[38:39], v[38:39], v[38:39], v[42:43]
	v_mov_b32_e32 v48, v29
	v_mov_b32_e32 v49, v33
	v_pk_fma_f32 v[42:43], v[46:47], v[46:47], v[44:45]
	v_pk_fma_f32 v[38:39], v[40:41], v[40:41], v[38:39]
	v_pk_fma_f32 v[40:41], v[48:49], v[48:49], v[42:43]
	v_add_f32_e32 v7, v38, v39
	v_add_f32_e32 v7, v7, v40
	v_add_f32_e32 v7, v7, v41
	ds_bpermute_b32 v9, v12, v7
	v_lshlrev_b64 v[38:39], 11, v[0:1]
	v_lshl_add_u64 v[38:39], s[84:85], 0, v[38:39]
	v_lshl_add_u64 v[40:41], v[38:39], 0, v[136:137]
	v_add_u32_e32 v0, s26, v0
	s_waitcnt lgkmcnt(0)
	v_add_f32_e32 v7, v7, v9
	ds_bpermute_b32 v9, v13, v7
	s_waitcnt lgkmcnt(0)
	v_add_f32_e32 v7, v7, v9
	s_nop 1
	v_add_f32_dpp v7, v7, v7 row_ror:8 row_mask:0xf bank_mask:0xf
	s_nop 1
	v_add_f32_dpp v7, v7, v7 row_ror:4 row_mask:0xf bank_mask:0xf
	s_nop 1
	v_add_f32_dpp v7, v7, v7 quad_perm:[2,3,0,1] row_mask:0xf bank_mask:0xf
	s_nop 1
	v_add_f32_dpp v7, v7, v7 quad_perm:[1,0,3,2] row_mask:0xf bank_mask:0xf
	v_fmamk_f32 v7, v7, 0x3a800000, v165
	v_mul_f32_e32 v9, 0x4b800000, v7
	v_cmp_gt_f32_e32 vcc, s2, v7
	s_nop 1
	v_cndmask_b32_e32 v7, v7, v9, vcc
	v_rsq_f32_e32 v7, v7
	v_mov_b32_e32 v9, v137
	v_mul_f32_e32 v1, 0x45800000, v7
	v_cndmask_b32_e32 v42, v7, v1, vcc
	v_pk_mul_f32 v[18:19], v[18:19], v[42:43] op_sel_hi:[1,0]
	v_pk_mul_f32 v[20:21], v[20:21], v[42:43] op_sel_hi:[1,0]
	s_waitcnt vmcnt(0)
	v_pk_mul_f32 v[18:19], v[34:35], v[18:19]
	v_pk_mul_f32 v[20:21], v[36:37], v[20:21]
	v_cvt_pk_bf16_f32 v18, v18, v19
	v_cvt_pk_bf16_f32 v19, v20, v21
	global_store_dwordx2 v[40:41], v[18:19], off
	global_load_dwordx4 v[18:21], v[2:3], off offset:1024
	v_pk_mul_f32 v[22:23], v[22:23], v[42:43] op_sel_hi:[1,0]
	v_pk_mul_f32 v[24:25], v[24:25], v[42:43] op_sel_hi:[1,0]
	v_mov_b32_e32 v7, v137
	v_lshl_add_u64 v[34:35], v[38:39], 0, v[6:7]
	v_cmp_lt_i32_e32 vcc, s3, v0
	s_or_b64 s[10:11], vcc, s[10:11]
	s_waitcnt vmcnt(0)
	v_pk_mul_f32 v[18:19], v[18:19], v[22:23]
	v_pk_mul_f32 v[20:21], v[20:21], v[24:25]
	v_cvt_pk_bf16_f32 v18, v18, v19
	v_cvt_pk_bf16_f32 v19, v20, v21
	global_store_dwordx2 v[34:35], v[18:19], off
	global_load_dwordx4 v[18:21], v[2:3], off offset:2048
	v_pk_mul_f32 v[24:25], v[26:27], v[42:43] op_sel_hi:[1,0]
	v_pk_mul_f32 v[26:27], v[28:29], v[42:43] op_sel_hi:[1,0]
	v_lshl_add_u64 v[22:23], v[38:39], 0, v[8:9]
	s_waitcnt vmcnt(0)
	v_pk_mul_f32 v[18:19], v[18:19], v[24:25]
	v_pk_mul_f32 v[20:21], v[26:27], v[20:21]
	v_cvt_pk_bf16_f32 v18, v18, v19
	v_cvt_pk_bf16_f32 v19, v20, v21
	global_store_dwordx2 v[22:23], v[18:19], off
	global_load_dwordx4 v[18:21], v[2:3], off offset:3072
	v_pk_mul_f32 v[24:25], v[30:31], v[42:43] op_sel_hi:[1,0]
	v_pk_mul_f32 v[26:27], v[32:33], v[42:43] op_sel_hi:[1,0]
	v_lshl_add_u64 v[22:23], v[38:39], 0, v[10:11]
	s_waitcnt vmcnt(0)
	v_pk_mul_f32 v[18:19], v[24:25], v[18:19]
	v_pk_mul_f32 v[20:21], v[26:27], v[20:21]
	v_cvt_pk_bf16_f32 v18, v18, v19
	v_cvt_pk_bf16_f32 v19, v20, v21
	global_store_dwordx2 v[22:23], v[18:19], off
	s_andn2_b64 exec, exec, s[10:11]
	s_cbranch_execnz .LBB0_180
